# P0: once-read f32 input streams (x rows, W_in blocks) loaded with the nt hint; on top of v52
# speedup vs baseline: 1.0311x; 1.0311x over previous
; #define GAS __attribute__((address_space(1)))
; __device__ __forceinline__ void p0_prologue(Frame& F, const Ptrs& P) {
;     ...
;     f32x4 va[4][4];
; #pragma unroll
;     for (int r = 0; r < 4; ++r) { const GAS f32x4* xr = (const GAS f32x4*)(P.x + (size_t)(gw + r * NGW) * DM) + lane;
; #pragma unroll
;         for (int j = 0; j < 4; ++j) va[r][j] = xr[64 * j]; }
;     for (int it = gw - (NGW >= 2048 ? NGW - SEQ * 8 / 64 : 0); it < SEQ * 8 / 64; it += NGW) if (it >= 0) {
;         const int idx = it * 64 + lane, t = idx >> 3, i = idx & 7;
;         const double inv = i == 0 ? 1.0 : i == 1 ? 0.19392274474868576 : i == 2 ? 0.03760603093086393 : i == 3 ? 0.007292664737217109 : i == 4 ? 0.001414213562373095 : i == 5 ? 0.0002742481756762073 : i == 6 ? 5.318295896944988e-05 : 1.031338537721246e-05;
;         double s, c; sincos_d((double)t * inv, s, c);
;         ROPE[idx] = (float)c; ROPE[SEQ * 8 + idx] = (float)s;
.LBB0_14:
	v_readlane_b32 s8, v252, 6
	v_readlane_b32 s9, v252, 7
	s_cmp_lt_i32 s8, 1
	s_cselect_b64 s[0:1], -1, 0
	s_cmp_gt_i32 s9, 0
	s_cselect_b64 s[2:3], -1, 0
	s_and_b64 s[0:1], s[0:1], s[2:3]
	s_andn2_b64 vcc, exec, s[0:1]
	v_readlane_b32 s10, v252, 8
	v_readlane_b32 s11, v252, 9
	v_writelane_b32 v252, s71, 13
	s_cbranch_vccnz .LBB0_215
	v_readlane_b32 s0, v252, 4
	s_lshl_b32 s0, s0, 3
	v_readlane_b32 s1, v252, 5
	s_add_i32 s70, s0, s1
	v_readlane_b32 s2, v252, 2
	s_ashr_i32 s71, s70, 31
	s_lshl_b32 s33, s2, 3
	s_lshl_b64 s[68:69], s[70:71], 12
	s_add_u32 s0, s16, s68
	v_mbcnt_lo_u32_b32 v128, -1, 0
	v_mbcnt_hi_u32_b32 v128, -1, v128
	s_addc_u32 s1, s17, s69
	v_ashrrev_i32_e32 v129, 31, v128
	s_add_i32 s76, s70, s33
	v_lshlrev_b64 v[130:131], 4, v[128:129]
	s_ashr_i32 s77, s76, 31
	v_lshl_add_u64 v[0:1], s[0:1], 0, v[130:131]
	s_lshl_b64 s[0:1], s[76:77], 12
	s_add_u32 s0, s16, s0
	s_addc_u32 s1, s17, s1
	s_add_i32 s74, s76, s33
	s_ashr_i32 s75, s74, 31
	global_load_dwordx4 v[60:63], v[0:1], off nt
	global_load_dwordx4 v[56:59], v[0:1], off offset:1024 nt
	global_load_dwordx4 v[52:55], v[0:1], off offset:2048 nt
	global_load_dwordx4 v[48:51], v[0:1], off offset:3072 nt
	v_lshl_add_u64 v[0:1], s[0:1], 0, v[130:131]
	s_lshl_b64 s[0:1], s[74:75], 12
	s_add_u32 s0, s16, s0
	s_addc_u32 s1, s17, s1
	s_add_i32 s72, s74, s33
	s_ashr_i32 s73, s72, 31
	global_load_dwordx4 v[44:47], v[0:1], off nt
	global_load_dwordx4 v[40:43], v[0:1], off offset:1024 nt
	global_load_dwordx4 v[36:39], v[0:1], off offset:2048 nt
	global_load_dwordx4 v[32:35], v[0:1], off offset:3072 nt
	v_lshl_add_u64 v[0:1], s[0:1], 0, v[130:131]
	s_lshl_b64 s[0:1], s[72:73], 12
	s_add_u32 s0, s16, s0
	s_addc_u32 s1, s17, s1
	global_load_dwordx4 v[28:31], v[0:1], off nt
	global_load_dwordx4 v[24:27], v[0:1], off offset:1024 nt
	global_load_dwordx4 v[20:23], v[0:1], off offset:2048 nt
	global_load_dwordx4 v[16:19], v[0:1], off offset:3072 nt
	v_lshl_add_u64 v[0:1], s[0:1], 0, v[130:131]
	global_load_dwordx4 v[12:15], v[0:1], off nt
	global_load_dwordx4 v[8:11], v[0:1], off offset:1024 nt
	global_load_dwordx4 v[4:7], v[0:1], off offset:2048 nt
	s_nop 0
	global_load_dwordx4 v[0:3], v[0:1], off offset:3072 nt
	s_add_i32 s0, s33, 0xfffffc00
	s_cmpk_gt_i32 s2, 0xff
	s_cselect_b32 s0, s0, 0
	s_sub_i32 s12, s70, s0
	s_cmpk_gt_i32 s12, 0x3ff
	s_cbranch_scc1 .LBB0_44
	v_and_b32_e32 v108, 7, v128
	s_add_u32 s0, s96, 0x100000
	v_mov_b32_e32 v64, 0x3ee5a0f4
	v_mov_b32_e32 v65, 0x3f0be218
	v_cmp_eq_u32_e32 vcc, 6, v108
	v_readlane_b32 s2, v252, 2
	s_addc_u32 s1, s97, 0
	v_cndmask_b32_e32 v65, v64, v65, vcc
	v_mov_b32_e32 v64, 0xe49b7c16
	v_mov_b32_e32 v66, 0x8e4aa32f
	s_lshl_b32 s13, s2, 9
	s_mov_b32 s2, 0x6dc9c883
	s_mov_b32 s4, 0x54442d18
	s_mov_b32 s6, 0x33145c07
	s_mov_b32 s8, 0xe733b81f
	v_cndmask_b32_e32 v64, v64, v66, vcc
	v_lshl_add_u32 v66, s12, 6, v128
	s_mov_b32 s3, 0x3fe45f30
	s_mov_b32 s5, 0xbff921fb
	s_mov_b32 s7, 0xbc91a626
	s_mov_b32 s9, 0xbd6ae7f3
	s_mov_b32 s11, 0x3d2ae7f3
	v_mov_b32_e32 v68, 0xf20d667d
	v_mov_b32_e32 v69, 0x3f31f91e
	v_mov_b32_e32 v70, 0x3fff3717
	v_mov_b32_e32 v71, 0x3f572ba4
	v_mov_b32_e32 v72, 0xc8c0acee
	v_mov_b32_e32 v73, 0x3f7ddee9
	v_mov_b32_e32 v74, 0x1f5fa45
	v_mov_b32_e32 v75, 0x3fa34119
	v_mov_b32_e32 v76, 0xe352b568
	v_mov_b32_e32 v77, 0x3fc8d275
	v_mov_b32_e32 v78, 0x13a86d09
	v_mov_b32_e32 v79, 0x3de61246
	v_mov_b32_e32 v80, 0x67f544e4
	v_mov_b32_e32 v81, 0xbe5ae645
	v_mov_b32_e32 v82, 0xa556c734
	v_mov_b32_e32 v83, 0x3ec71de3
	v_mov_b32_e32 v84, 0x1a01a01a
	v_mov_b32_e32 v85, 0xbf2a01a0
	v_mov_b32_e32 v86, 0x11111111
	v_mov_b32_e32 v87, 0x3f811111
	v_mov_b32_e32 v88, 0x55555555
	v_mov_b32_e32 v89, 0xbfc55555
	v_mov_b32_e32 v90, 0xa8c07c9d
	v_mov_b32_e32 v91, 0xbda93974
	v_mov_b32_e32 v92, 0xeff8d898
	v_mov_b32_e32 v93, 0x3e21eed8
	v_mov_b32_e32 v94, 0xb7789f5c
	v_mov_b32_e32 v95, 0xbe927e4f
	v_mov_b32_e32 v97, 0x3efa01a0
	v_mov_b32_e32 v98, 0x16c16c17
	v_mov_b32_e32 v99, 0xbf56c16c
	v_mov_b32_e32 v101, 0x3fa55555
	s_branch .LBB0_20

; #define GAS __attribute__((address_space(1)))
; __device__ __forceinline__ void p0_item_load(const P0Item& I, float (&wv)[32], int lane) {
; #pragma unroll
;     for (int i = 0; i < 8; ++i) { const int kk = 8 * i + (lane >> 3); const f32x4 v = *(const GAS f32x4*)(I.W + (size_t)(I.k0 + kk) * I.ldw + I.src0 + 4 * (lane & 7));
;         wv[4 * i] = v.x; wv[4 * i + 1] = v.y; wv[4 * i + 2] = v.z; wv[4 * i + 3] = v.w; }
; }
.LBB0_61:
	s_add_i32 s10, s33, s64
	s_cmpk_lt_i32 s10, 0xa10
	s_cselect_b64 s[90:91], -1, 0
	s_lshl_b32 s86, s9, 6
	s_ashr_i32 s9, s8, 31
	v_add_u32_e32 v138, s86, v132
	s_waitcnt vmcnt(0)
	v_lshl_add_u64 v[96:97], s[8:9], 2, v[136:137]
	v_add_u32_e32 v100, 8, v138
	v_mad_i64_i32 v[98:99], s[8:9], v138, s61, v[96:97]
	v_mad_i64_i32 v[100:101], s[8:9], v100, s61, v[96:97]
	global_load_dwordx4 v[124:127], v[98:99], off nt
	global_load_dwordx4 v[120:123], v[100:101], off nt
	v_add_u32_e32 v98, 16, v138
	v_add_u32_e32 v100, 24, v138
	v_mad_i64_i32 v[98:99], s[8:9], v98, s61, v[96:97]
	v_mad_i64_i32 v[100:101], s[8:9], v100, s61, v[96:97]
	global_load_dwordx4 v[116:119], v[98:99], off nt
	global_load_dwordx4 v[112:115], v[100:101], off nt
	v_add_u32_e32 v98, 32, v138
	v_add_u32_e32 v100, 40, v138
	v_mad_i64_i32 v[98:99], s[8:9], v98, s61, v[96:97]
	v_mad_i64_i32 v[100:101], s[8:9], v100, s61, v[96:97]
	global_load_dwordx4 v[108:111], v[98:99], off nt
	global_load_dwordx4 v[104:107], v[100:101], off nt
	v_add_u32_e32 v98, 48, v138
	v_add_u32_e32 v100, 56, v138
	v_mad_i64_i32 v[98:99], s[8:9], v98, s61, v[96:97]
	v_mad_i64_i32 v[96:97], s[8:9], v100, s61, v[96:97]
	global_load_dwordx4 v[100:103], v[98:99], off nt
	s_nop 0
	global_load_dwordx4 v[96:99], v[96:97], off nt
	s_cmpk_gt_i32 s10, 0xa0f
	s_cbranch_scc1 .LBB0_75
	s_mul_hi_i32 s8, s10, 0xcb8727c1
	s_add_i32 s8, s8, s10
	s_lshr_b32 s9, s8, 31
	s_ashr_i32 s8, s8, 7
	s_add_i32 s9, s8, s9
	s_mul_i32 s8, s9, 0xa1
	s_sub_i32 s82, s10, s8
	s_lshl_b32 s65, s82, 5
	s_mov_b64 s[80:81], 0
	s_cmpk_lt_i32 s82, 0x50
	s_mov_b32 s8, s65
	s_cbranch_scc1 .LBB0_74
	s_cmpk_gt_u32 s82, 0x6f
	s_mov_b64 s[10:11], -1
	s_cbranch_scc0 .LBB0_72
	s_cmpk_gt_u32 s82, 0x77
	s_mov_b64 s[14:15], -1
	s_cbranch_scc0 .LBB0_70
	s_cmpk_gt_u32 s82, 0x7f
	s_cbranch_scc0 .LBB0_67
	s_add_i32 s8, s65, 32
	s_cmpk_lt_u32 s82, 0xa0
	s_cselect_b32 s8, s8, 0xa00
	s_mov_b64 s[10:11], 0

; #define GAS __attribute__((address_space(1)))
; __device__ __forceinline__ void p0_item_load(const P0Item& I, float (&wv)[32], int lane) {
; #pragma unroll
;     for (int i = 0; i < 8; ++i) { const int kk = 8 * i + (lane >> 3); const f32x4 v = *(const GAS f32x4*)(I.W + (size_t)(I.k0 + kk) * I.ldw + I.src0 + 4 * (lane & 7));
;         wv[4 * i] = v.x; wv[4 * i + 1] = v.y; wv[4 * i + 2] = v.z; wv[4 * i + 3] = v.w; }
; }
.LBB0_74:
	s_lshl_b32 s82, s9, 6
	s_ashr_i32 s9, s8, 31
	v_add_u32_e32 v92, s82, v132
	v_lshl_add_u64 v[88:89], s[8:9], 2, v[136:137]
	v_mad_i64_i32 v[64:65], s[8:9], v92, s61, v[88:89]
	v_add_u32_e32 v66, 8, v92
	v_add_u32_e32 v72, 16, v92
	v_add_u32_e32 v74, 24, v92
	v_add_u32_e32 v80, 32, v92
	v_add_u32_e32 v82, 40, v92
	v_add_u32_e32 v90, 48, v92
	v_add_u32_e32 v92, 56, v92
	v_mad_i64_i32 v[66:67], s[8:9], v66, s61, v[88:89]
	v_mad_i64_i32 v[72:73], s[8:9], v72, s61, v[88:89]
	v_mad_i64_i32 v[74:75], s[8:9], v74, s61, v[88:89]
	v_mad_i64_i32 v[80:81], s[8:9], v80, s61, v[88:89]
	v_mad_i64_i32 v[82:83], s[8:9], v82, s61, v[88:89]
	v_mad_i64_i32 v[90:91], s[8:9], v90, s61, v[88:89]
	v_mad_i64_i32 v[88:89], s[8:9], v92, s61, v[88:89]
	global_load_dwordx4 v[68:71], v[64:65], off nt
	s_nop 0
	global_load_dwordx4 v[64:67], v[66:67], off nt
	s_nop 0
	global_load_dwordx4 v[76:79], v[72:73], off nt
	s_nop 0
	global_load_dwordx4 v[72:75], v[74:75], off nt
	s_nop 0
	global_load_dwordx4 v[84:87], v[80:81], off nt
	s_nop 0
	global_load_dwordx4 v[80:83], v[82:83], off nt
	s_nop 0
	global_load_dwordx4 v[92:95], v[90:91], off nt
	s_nop 0
	global_load_dwordx4 v[88:91], v[88:89], off nt

; #define GAS __attribute__((address_space(1)))
; __device__ __forceinline__ void p0_item_load(const P0Item& I, float (&wv)[32], int lane) {
; #pragma unroll
;     for (int i = 0; i < 8; ++i) { const int kk = 8 * i + (lane >> 3); const f32x4 v = *(const GAS f32x4*)(I.W + (size_t)(I.k0 + kk) * I.ldw + I.src0 + 4 * (lane & 7));
;         wv[4 * i] = v.x; wv[4 * i + 1] = v.y; wv[4 * i + 2] = v.z; wv[4 * i + 3] = v.w; }
; }
.LBB0_96:
	s_lshl_b32 s86, s11, 6
	v_add_u32_e32 v102, s86, v132
	s_ashr_i32 s11, s10, 31
	v_lshl_add_u64 v[96:97], s[10:11], 2, v[136:137]
	v_add_u32_e32 v100, 8, v102
	v_mad_i64_i32 v[98:99], s[10:11], v102, s61, v[96:97]
	v_mad_i64_i32 v[100:101], s[10:11], v100, s61, v[96:97]
	global_load_dwordx4 v[124:127], v[98:99], off nt
	global_load_dwordx4 v[120:123], v[100:101], off nt
	v_add_u32_e32 v98, 16, v102
	v_add_u32_e32 v100, 24, v102
	v_mad_i64_i32 v[98:99], s[10:11], v98, s61, v[96:97]
	v_mad_i64_i32 v[100:101], s[10:11], v100, s61, v[96:97]
	global_load_dwordx4 v[116:119], v[98:99], off nt
	global_load_dwordx4 v[112:115], v[100:101], off nt
	v_add_u32_e32 v98, 32, v102
	v_add_u32_e32 v100, 40, v102
	v_mad_i64_i32 v[98:99], s[10:11], v98, s61, v[96:97]
	v_mad_i64_i32 v[100:101], s[10:11], v100, s61, v[96:97]
	global_load_dwordx4 v[108:111], v[98:99], off nt
	global_load_dwordx4 v[104:107], v[100:101], off nt
	v_add_u32_e32 v98, 48, v102
	v_add_u32_e32 v100, 56, v102
	v_mad_i64_i32 v[98:99], s[10:11], v98, s61, v[96:97]
	v_mad_i64_i32 v[96:97], s[10:11], v100, s61, v[96:97]
	global_load_dwordx4 v[100:103], v[98:99], off nt
	s_nop 0
	global_load_dwordx4 v[96:99], v[96:97], off nt
	s_andn2_b64 vcc, exec, s[90:91]
	s_cbranch_vccz .LBB0_99

; #define GAS __attribute__((address_space(1)))
; __device__ __forceinline__ void p0_prologue(Frame& F, const Ptrs& P) {
;     ...
;     {
;         f32x4 vb[4][4];
; #pragma unroll
;         for (int r = 0; r < 4; ++r) { const GAS f32x4* xr = (const GAS f32x4*)(P.x + (size_t)(gw + (4 + r) * NGW) * DM) + lane;
; #pragma unroll
;             for (int j = 0; j < 4; ++j) vb[r][j] = xr[64 * j]; }
;         P0_XROWS(va, gw);
;         P0_XROWS(vb, gw + 4 * NGW);
.LBB0_131:
	s_add_u32 s14, s96, 0x180000
	s_addc_u32 s15, s97, 0
	s_add_u32 s20, s96, 0x1400000
	v_readlane_b32 s0, v252, 2
	s_addc_u32 s21, s97, 0
	s_lshl_b32 s0, s0, 5
	s_add_i32 s6, s70, s0
	s_ashr_i32 s7, s6, 31
	s_lshl_b64 s[0:1], s[6:7], 12
	s_add_u32 s0, s16, s0
	s_addc_u32 s1, s17, s1
	s_add_i32 s8, s6, s33
	s_ashr_i32 s9, s8, 31
	v_lshl_add_u64 v[64:65], s[0:1], 0, v[130:131]
	s_lshl_b64 s[0:1], s[8:9], 12
	s_add_u32 s0, s16, s0
	s_addc_u32 s1, s17, s1
	global_load_dwordx4 v[124:127], v[64:65], off nt
	global_load_dwordx4 v[120:123], v[64:65], off offset:1024 nt
	global_load_dwordx4 v[116:119], v[64:65], off offset:2048 nt
	global_load_dwordx4 v[112:115], v[64:65], off offset:3072 nt
	v_lshl_add_u64 v[64:65], s[0:1], 0, v[130:131]
	s_add_i32 s0, s8, s33
	s_ashr_i32 s1, s0, 31
	s_lshl_b64 s[2:3], s[0:1], 12
	s_add_u32 s2, s16, s2
	s_addc_u32 s3, s17, s3
	s_add_i32 s0, s0, s33
	s_ashr_i32 s1, s0, 31
	s_lshl_b64 s[0:1], s[0:1], 12
	s_add_u32 s0, s16, s0
	global_load_dwordx4 v[108:111], v[64:65], off nt
	global_load_dwordx4 v[104:107], v[64:65], off offset:1024 nt
	global_load_dwordx4 v[100:103], v[64:65], off offset:2048 nt
	global_load_dwordx4 v[96:99], v[64:65], off offset:3072 nt
	v_lshl_add_u64 v[64:65], s[2:3], 0, v[130:131]
	s_addc_u32 s1, s17, s1
	global_load_dwordx4 v[92:95], v[64:65], off nt
	global_load_dwordx4 v[88:91], v[64:65], off offset:1024 nt
	global_load_dwordx4 v[84:87], v[64:65], off offset:2048 nt
	global_load_dwordx4 v[80:83], v[64:65], off offset:3072 nt
	v_lshl_add_u64 v[64:65], s[0:1], 0, v[130:131]
	global_load_dwordx4 v[76:79], v[64:65], off nt
	global_load_dwordx4 v[72:75], v[64:65], off offset:1024 nt
	global_load_dwordx4 v[68:71], v[64:65], off offset:2048 nt
	s_nop 0
	global_load_dwordx4 v[64:67], v[64:65], off offset:3072 nt
	s_waitcnt vmcnt(31)
	v_mul_f32_e32 v132, v61, v61
	v_mul_f32_e32 v133, v63, v63
	v_fmac_f32_e32 v132, v60, v60
	v_fmac_f32_e32 v133, v62, v62
	v_add_f32_e32 v132, v132, v133
	s_waitcnt vmcnt(30)
	v_mul_f32_e32 v133, v57, v57
	v_mul_f32_e32 v135, v59, v59
	v_fmac_f32_e32 v133, v56, v56
	v_fmac_f32_e32 v135, v58, v58
	v_add_f32_e32 v133, v133, v135
	v_mbcnt_lo_u32_b32 v130, -1, 0
	v_add_f32_e32 v132, v132, v133
	s_waitcnt vmcnt(29)
	v_mul_f32_e32 v133, v53, v53
	v_mul_f32_e32 v135, v55, v55
	v_mbcnt_hi_u32_b32 v134, -1, v130
	v_fmac_f32_e32 v133, v52, v52
	v_fmac_f32_e32 v135, v54, v54
	v_and_b32_e32 v130, 64, v134
	v_add_f32_e32 v133, v133, v135
	v_add_u32_e32 v136, 64, v130
	v_xor_b32_e32 v130, 1, v134
	v_add_f32_e32 v132, v132, v133
	s_waitcnt vmcnt(28)
	v_mul_f32_e32 v133, v49, v49
	v_mul_f32_e32 v135, v51, v51
	v_cmp_lt_i32_e32 vcc, v130, v136
	v_fmac_f32_e32 v133, v48, v48
	v_fmac_f32_e32 v135, v50, v50
	v_cndmask_b32_e32 v130, v134, v130, vcc
	v_add_f32_e32 v133, v133, v135
	v_lshlrev_b32_e32 v130, 2, v130
	v_add_f32_e32 v132, v132, v133
	ds_bpermute_b32 v133, v130, v132
	v_xor_b32_e32 v131, 2, v134
	v_cmp_lt_i32_e32 vcc, v131, v136
	v_xor_b32_e32 v135, 4, v134
	v_bfe_u32 v140, v60, 16, 1
	v_cndmask_b32_e32 v131, v134, v131, vcc
	v_lshlrev_b32_e32 v131, 2, v131
	s_waitcnt lgkmcnt(0)
	v_add_f32_e32 v133, v132, v133
	ds_bpermute_b32 v137, v131, v133
	v_cmp_lt_i32_e32 vcc, v135, v136
	s_movk_i32 s16, 0x7fff
	v_add3_u32 v60, v60, v140, s16
	v_cndmask_b32_e32 v132, v134, v135, vcc
	v_lshlrev_b32_e32 v132, 2, v132
	s_waitcnt lgkmcnt(0)
	v_add_f32_e32 v137, v133, v137
	ds_bpermute_b32 v138, v132, v137
	v_xor_b32_e32 v135, 8, v134
	v_cmp_lt_i32_e32 vcc, v135, v136
	v_bfe_u32 v140, v61, 16, 1
	v_lshrrev_b32_e32 v60, 16, v60
	v_cndmask_b32_e32 v133, v134, v135, vcc
	v_lshlrev_b32_e32 v133, 2, v133
	s_waitcnt lgkmcnt(0)
	v_add_f32_e32 v137, v137, v138
	ds_bpermute_b32 v138, v133, v137
	v_xor_b32_e32 v135, 16, v134
	v_cmp_lt_i32_e32 vcc, v135, v136
	v_add3_u32 v61, v61, v140, s16
	s_mov_b32 s17, 0xffff0000
	v_cndmask_b32_e32 v135, v134, v135, vcc
	v_lshlrev_b32_e32 v135, 2, v135
	s_waitcnt lgkmcnt(0)
	v_add_f32_e32 v137, v137, v138
	ds_bpermute_b32 v138, v135, v137
	s_lshl_b64 s[4:5], s[70:71], 11
	v_and_or_b32 v60, v61, s17, v60
	v_bfe_u32 v61, v62, 16, 1
	v_xor_b32_e32 v139, 32, v134
	s_add_u32 s2, s20, s4
	v_add3_u32 v61, v62, v61, s16
	v_bfe_u32 v62, v63, 16, 1
	v_cmp_lt_i32_e32 vcc, v139, v136
	s_addc_u32 s3, s21, s5
	v_lshrrev_b32_e32 v61, 16, v61
	v_add3_u32 v62, v63, v62, s16
	v_cndmask_b32_e32 v134, v134, v139, vcc
	s_waitcnt lgkmcnt(0)
	v_add_f32_e32 v136, v137, v138
	v_lshl_add_u64 v[138:139], v[128:129], 3, s[2:3]
	v_and_or_b32 v61, v62, s17, v61
	global_store_dwordx2 v[138:139], v[60:61], off
	v_bfe_u32 v60, v56, 16, 1
	v_add3_u32 v56, v56, v60, s16
	v_bfe_u32 v60, v57, 16, 1
	v_lshrrev_b32_e32 v56, 16, v56
	v_add3_u32 v57, v57, v60, s16
	v_and_or_b32 v56, v57, s17, v56
	v_bfe_u32 v57, v58, 16, 1
	v_add3_u32 v57, v58, v57, s16
	v_bfe_u32 v58, v59, 16, 1
	v_lshrrev_b32_e32 v57, 16, v57
	v_add3_u32 v58, v59, v58, s16
	v_and_or_b32 v57, v58, s17, v57
	global_store_dwordx2 v[138:139], v[56:57], off offset:512
	v_bfe_u32 v56, v52, 16, 1
	v_add3_u32 v52, v52, v56, s16
	v_bfe_u32 v56, v53, 16, 1
	v_lshrrev_b32_e32 v52, 16, v52
	v_add3_u32 v53, v53, v56, s16
	v_and_or_b32 v52, v53, s17, v52
	v_bfe_u32 v53, v54, 16, 1
	v_add3_u32 v53, v54, v53, s16
	v_bfe_u32 v54, v55, 16, 1
	v_lshrrev_b32_e32 v53, 16, v53
	v_add3_u32 v54, v55, v54, s16
	v_and_or_b32 v53, v54, s17, v53
	global_store_dwordx2 v[138:139], v[52:53], off offset:1024
	v_bfe_u32 v52, v48, 16, 1
	v_lshlrev_b32_e32 v134, 2, v134
	v_add3_u32 v48, v48, v52, s16
	v_bfe_u32 v52, v49, 16, 1
	ds_bpermute_b32 v137, v134, v136
	v_lshrrev_b32_e32 v48, 16, v48
	v_add3_u32 v49, v49, v52, s16
	v_and_or_b32 v48, v49, s17, v48
	v_bfe_u32 v49, v50, 16, 1
	v_add3_u32 v49, v50, v49, s16
	v_bfe_u32 v50, v51, 16, 1
	v_lshrrev_b32_e32 v49, 16, v49
	v_add3_u32 v50, v51, v50, s16
	v_cmp_eq_u32_e64 s[0:1], 0, v128
	v_and_or_b32 v49, v50, s17, v49
	global_store_dwordx2 v[138:139], v[48:49], off offset:1536
	s_and_saveexec_b64 s[10:11], s[0:1]
	s_cbranch_execz .LBB0_133
	s_waitcnt lgkmcnt(0)
	v_add_f32_e32 v48, v136, v137
	v_mov_b32_e32 v49, 0x358637bd
	v_fmac_f32_e32 v49, 0x3a800000, v48
	s_mov_b32 s2, 0xf800000
	v_mul_f32_e32 v48, 0x4f800000, v49
	v_cmp_gt_f32_e32 vcc, s2, v49
	s_nop 1
	v_cndmask_b32_e32 v48, v49, v48, vcc
	v_sqrt_f32_e32 v49, v48
	s_nop 0
	v_add_u32_e32 v50, -1, v49
	v_fma_f32 v51, -v50, v49, v48
	v_cmp_ge_f32_e64 s[2:3], 0, v51
	v_add_u32_e32 v51, 1, v49
	s_nop 0
	v_cndmask_b32_e64 v50, v49, v50, s[2:3]
	v_fma_f32 v49, -v51, v49, v48
	v_cmp_lt_f32_e64 s[2:3], 0, v49
	s_nop 1
	v_cndmask_b32_e64 v49, v50, v51, s[2:3]
	v_mul_f32_e32 v50, 0x37800000, v49
	v_cndmask_b32_e32 v49, v49, v50, vcc
	v_mov_b32_e32 v50, 0x260
	v_cmp_class_f32_e32 vcc, v48, v50
	s_nop 1
	v_cndmask_b32_e32 v48, v49, v48, vcc
	v_div_scale_f32 v49, s[2:3], v48, v48, 1.0
	v_rcp_f32_e32 v50, v49
	s_lshl_b64 s[2:3], s[70:71], 2
	s_add_u32 s2, s14, s2
	s_addc_u32 s3, s15, s3
	v_fma_f32 v51, -v49, v50, 1.0
	v_fmac_f32_e32 v50, v51, v50
	v_div_scale_f32 v51, vcc, 1.0, v48, 1.0
	v_mul_f32_e32 v52, v51, v50
	v_fma_f32 v53, -v49, v52, v51
	v_fmac_f32_e32 v52, v53, v50
	v_fma_f32 v49, -v49, v52, v51
	v_div_fmas_f32 v49, v49, v50, v52
	v_div_fixup_f32 v48, v49, v48, 1.0
	v_mov_b32_e32 v49, 0
	global_store_dword v49, v48, s[2:3]
